# XR K-loops: wave-uniform strip tests done with s_cmp_eq_u64, the VALU mask derivation moved behind the segment's closing barrier
# baseline (speedup 1.0000x reference)
; #define PG8_LDX(b) do { if constexpr (XR) { _Pragma("unroll") for (int k = 0; k < 2; ++k) Ax_[k] = *(const PG8_LAS bf16x8*)(lds + XR_OFF + (b) * 2048 + aoffx + k * 1024); } } while (0)
; #define PG8_MMAX() do { if constexpr (XR) { if (hasx) { __builtin_amdgcn_s_setprio(1); if (wr == 0) PG8_MMAX_(B0); else PG8_MMAX_(B1); __builtin_amdgcn_s_setprio(0); } } } while (0)
; #define PG8_WAIT_LOOP() do { if constexpr (XR) PG8_WAIT_V(9); else PG8_WAIT_V(8); } while (0)
; #define PG8_STAGE(bufoff, gbase, voff) do { _Pragma("unroll") for (int _i = 0; _i < 2; ++_i) \
;         __builtin_amdgcn_global_load_lds((const unsigned*)((const char*)(gbase) + (voff)[_i]), (PG8_LAS unsigned*)(lds + (bufoff) + ldsw + _i * 8192), 16, 0, 0); } while (0)
; #define PG8_LDA(dst, b, h) do { _Pragma("unroll") for (int m = 0; m < 4; ++m) _Pragma("unroll") for (int k = 0; k < 2; ++k) dst[m][k] = *(const PG8_LAS bf16x8*)(lds + PG8_SA(b, h) + aoff + m * 2048 + k * 1024); } while (0)
; #define PG8_LDB(dst, b, h) do { _Pragma("unroll") for (int n = 0; n < 2; ++n) _Pragma("unroll") for (int k = 0; k < 2; ++k) dst[n][k] = *(const PG8_LAS bf16x8*)(lds + PG8_SB(b, h) + boff + n * 2048 + k * 1024); } while (0)
; #define PG8_MMA(ai, bj, At, Bt) do { __builtin_amdgcn_s_setprio(1); _Pragma("unroll") for (int m = 0; m < 4; ++m) _Pragma("unroll") for (int n = 0; n < 2; ++n) _Pragma("unroll") for (int k = 0; k < 2; ++k) \
;         acc[ai][bj][m][n] = __builtin_amdgcn_mfma_f32_16x16x32_bf16(Bt[n][k], At[m][k], acc[ai][bj][m][n], 0, 0, 0); __builtin_amdgcn_s_setprio(0); } while (0)
; #define PG8_WAIT_L(n) asm volatile("s_waitcnt lgkmcnt(" #n ")" ::: "memory")
; #define PG8_BAR __builtin_amdgcn_s_barrier()
; #define PG8_SCHED __builtin_amdgcn_sched_barrier(0)
; template <class Epi, class Sched, bool ALIGN_EPI = false, bool SP2 = false, bool DRAIN = true, bool XR = false>
; __device__ __forceinline__ void gemm_phase(PG8_LAS unsigned char* lds, const Gemm g, const Sched& S, const Epi& E) {
;     ...
;             PG8_LDB(B0, 0, 0); PG8_LDB(B1, 0, 1); PG8_SCHED; PG8_LDA(At, 0, 0); PG8_LDX(0); PG8_STAGE(PG8_SA(1, 1), a1 + hstepA, voffA);
;             PG8_WAIT_LOOP(); PG8_WAIT_L(0); PG8_BAR; PG8_MMA(0, 0, At, B0); PG8_MMA(0, 1, At, B1); PG8_MMAX(); PG8_BAR; PG8_SCHED;
.LBB0_1220:
	v_add_u32_e32 v4, 0x10000, v250
	ds_read_b128 v[158:161], v4
	ds_read_b128 v[162:165], v4 offset:1024
	ds_read_b128 v[166:169], v4 offset:2048
	ds_read_b128 v[170:173], v4 offset:3072
	v_add_u32_e32 v4, 0x14000, v250
	s_and_b32 s8, s50, s82
	ds_read_b128 v[142:145], v4
	ds_read_b128 v[146:149], v4 offset:1024
	ds_read_b128 v[150:153], v4 offset:2048
	ds_read_b128 v[154:157], v4 offset:3072
	s_lshr_b32 s84, s8, 2
	s_lshl_b32 s8, s8, 7
	s_lshl_b64 s[6:7], s[84:85], 9
	s_and_b32 s8, s8, 0x100
	s_add_u32 s6, s18, s6
	s_addc_u32 s7, s19, s7
	s_add_u32 s6, s6, s8
	s_addc_u32 s7, s7, 0
	s_add_u32 s6, s6, s10
	v_add_u32_e32 v4, 0x22400, v240
	s_addc_u32 s7, s7, s11
	ds_read_b128 v[182:185], v251
	ds_read_b128 v[186:189], v251 offset:1024
	ds_read_b128 v[190:193], v251 offset:2048
	ds_read_b128 v[194:197], v251 offset:3072
	ds_read_b128 v[198:201], v251 offset:4096
	ds_read_b128 v[202:205], v251 offset:5120
	ds_read_b128 v[224:227], v251 offset:6144
	ds_read_b128 v[228:231], v251 offset:7168
	ds_read_b128 v[174:177], v4
	ds_read_b128 v[178:181], v4 offset:1024
	v_lshl_add_u64 v[4:5], s[6:7], 0, v[214:215]
	v_lshl_add_u64 v[4:5], v[4:5], 0, s[86:87]
	s_add_i32 m0, s64, 0xc000
	s_nop 0
	global_load_lds_dwordx4 v[4:5], off
	v_lshl_add_u64 v[4:5], s[6:7], 0, v[218:219]
	v_lshl_add_u64 v[4:5], v[4:5], 0, s[86:87]
	s_add_i32 m0, s64, 0xe000
	s_nop 0
	global_load_lds_dwordx4 v[4:5], off
	s_waitcnt vmcnt(9)
	s_waitcnt lgkmcnt(0)
	s_barrier
	v_mfma_f32_16x16x32_bf16 v[138:141], v[158:161], v[182:185], v[138:141]
	v_mfma_f32_16x16x32_bf16 v[134:137], v[166:169], v[182:185], v[134:137]
	v_mfma_f32_16x16x32_bf16 v[130:133], v[158:161], v[190:193], v[130:133]
	v_mfma_f32_16x16x32_bf16 v[126:129], v[166:169], v[190:193], v[126:129]
	v_mfma_f32_16x16x32_bf16 v[122:125], v[158:161], v[198:201], v[122:125]
	v_mfma_f32_16x16x32_bf16 v[118:121], v[166:169], v[198:201], v[118:121]
	v_mfma_f32_16x16x32_bf16 v[114:117], v[158:161], v[224:227], v[114:117]
	v_mfma_f32_16x16x32_bf16 v[110:113], v[166:169], v[224:227], v[110:113]
	v_mfma_f32_16x16x32_bf16 v[138:141], v[162:165], v[186:189], v[138:141]
	v_mfma_f32_16x16x32_bf16 v[134:137], v[170:173], v[186:189], v[134:137]
	v_mfma_f32_16x16x32_bf16 v[130:133], v[162:165], v[194:197], v[130:133]
	v_mfma_f32_16x16x32_bf16 v[126:129], v[170:173], v[194:197], v[126:129]
	v_mfma_f32_16x16x32_bf16 v[122:125], v[162:165], v[202:205], v[122:125]
	v_mfma_f32_16x16x32_bf16 v[118:121], v[170:173], v[202:205], v[118:121]
	v_mfma_f32_16x16x32_bf16 v[114:117], v[162:165], v[228:231], v[114:117]
	v_mfma_f32_16x16x32_bf16 v[110:113], v[170:173], v[228:231], v[110:113]
	v_mfma_f32_16x16x32_bf16 v[106:109], v[142:145], v[182:185], v[106:109]
	v_mfma_f32_16x16x32_bf16 v[102:105], v[150:153], v[182:185], v[102:105]
	v_mfma_f32_16x16x32_bf16 v[98:101], v[142:145], v[190:193], v[98:101]
	v_mfma_f32_16x16x32_bf16 v[94:97], v[150:153], v[190:193], v[94:97]
	v_mfma_f32_16x16x32_bf16 v[90:93], v[142:145], v[198:201], v[90:93]
	v_mfma_f32_16x16x32_bf16 v[86:89], v[150:153], v[198:201], v[86:89]
	v_mfma_f32_16x16x32_bf16 v[82:85], v[142:145], v[224:227], v[82:85]
	v_mfma_f32_16x16x32_bf16 v[78:81], v[150:153], v[224:227], v[78:81]
	v_mfma_f32_16x16x32_bf16 v[106:109], v[146:149], v[186:189], v[106:109]
	v_mfma_f32_16x16x32_bf16 v[102:105], v[154:157], v[186:189], v[102:105]
	v_mfma_f32_16x16x32_bf16 v[98:101], v[146:149], v[194:197], v[98:101]
	v_mfma_f32_16x16x32_bf16 v[94:97], v[154:157], v[194:197], v[94:97]
	v_mfma_f32_16x16x32_bf16 v[90:93], v[146:149], v[202:205], v[90:93]
	v_mfma_f32_16x16x32_bf16 v[86:89], v[154:157], v[202:205], v[86:89]
	v_mfma_f32_16x16x32_bf16 v[82:85], v[146:149], v[228:231], v[82:85]
	v_mfma_f32_16x16x32_bf16 v[78:81], v[154:157], v[228:231], v[78:81]
	s_cmp_eq_u64 s[22:23], 0
	s_cbranch_scc1 .LBB0_1226
	s_mov_b64 s[48:49], -1
	s_cmp_eq_u64 s[40:41], 0
	s_cbranch_scc1 .LBB0_1223
	v_mfma_f32_16x16x32_bf16 v[10:13], v[142:145], v[174:177], v[10:13]
	s_mov_b64 s[48:49], 0
	v_mfma_f32_16x16x32_bf16 v[6:9], v[150:153], v[174:177], v[6:9]
	v_mfma_f32_16x16x32_bf16 v[10:13], v[146:149], v[178:181], v[10:13]
	v_mfma_f32_16x16x32_bf16 v[6:9], v[154:157], v[178:181], v[6:9]

; #define PG8_STAGEX(b, gbase) do { if constexpr (XR) { if (lane < 16) __builtin_amdgcn_global_load_lds((const unsigned*)((const char*)(gbase) + voffX), (PG8_LAS unsigned*)(lds + XR_OFF + (b) * 2048 + wid * 256), 16, 0, 0); } } while (0)
; #define PG8_MMAX() do { if constexpr (XR) { if (hasx) { __builtin_amdgcn_s_setprio(1); if (wr == 0) PG8_MMAX_(B0); else PG8_MMAX_(B1); __builtin_amdgcn_s_setprio(0); } } } while (0)
; #define PG8_WAIT_LOOP() do { if constexpr (XR) PG8_WAIT_V(9); else PG8_WAIT_V(8); } while (0)
; #define PG8_STAGE(bufoff, gbase, voff) do { _Pragma("unroll") for (int _i = 0; _i < 2; ++_i) \
;         __builtin_amdgcn_global_load_lds((const unsigned*)((const char*)(gbase) + (voff)[_i]), (PG8_LAS unsigned*)(lds + (bufoff) + ldsw + _i * 8192), 16, 0, 0); } while (0)
; #define PG8_LDA(dst, b, h) do { _Pragma("unroll") for (int m = 0; m < 4; ++m) _Pragma("unroll") for (int k = 0; k < 2; ++k) dst[m][k] = *(const PG8_LAS bf16x8*)(lds + PG8_SA(b, h) + aoff + m * 2048 + k * 1024); } while (0)
; #define PG8_MMA(ai, bj, At, Bt) do { __builtin_amdgcn_s_setprio(1); _Pragma("unroll") for (int m = 0; m < 4; ++m) _Pragma("unroll") for (int n = 0; n < 2; ++n) _Pragma("unroll") for (int k = 0; k < 2; ++k) \
;         acc[ai][bj][m][n] = __builtin_amdgcn_mfma_f32_16x16x32_bf16(Bt[n][k], At[m][k], acc[ai][bj][m][n], 0, 0, 0); __builtin_amdgcn_s_setprio(0); } while (0)
; #define PG8_WAIT_L(n) asm volatile("s_waitcnt lgkmcnt(" #n ")" ::: "memory")
; #define PG8_BAR __builtin_amdgcn_s_barrier()
; template <class Epi, class Sched, bool ALIGN_EPI = false, bool SP2 = false, bool DRAIN = true, bool XR = false>
; __device__ __forceinline__ void gemm_phase(PG8_LAS unsigned char* lds, const Gemm g, const Sched& S, const Epi& E) {
;     ...
;             const char* a1 = cA + PG8_KOA(t) + kstep;
;             const char* a2 = last ? nA + ka0 : cA + PG8_KOA(t + 2); const char* b2 = last ? nB + kb0 : cB + PG8_KOB(t + 2);
;             const char* x2 = XR ? (last ? nX + kx0 : cX + PG8_KOX(t + 2)) : nullptr; const char* x3 = XR ? x2 + kstep : nullptr;
;     ...
;             PG8_WAIT_LOOP(); PG8_WAIT_L(0); PG8_BAR; PG8_MMA(0, 0, At, B0); PG8_MMA(0, 1, At, B1); PG8_MMAX(); PG8_BAR; PG8_SCHED;
;             PG8_LDA(At, 0, 1); PG8_STAGE(PG8_SB(0, 0), b2, voffB); PG8_STAGE(PG8_SB(0, 1), b2 + hstep, voffB); PG8_STAGE(PG8_SA(0, 0), a2, voffA); PG8_STAGEX(0, x2);
.LBB0_1225:
.LBB0_1226:
	s_barrier
	v_cndmask_b32_e64 v4, 0, 1, s[22:23]
	v_cmp_ne_u32_e64 s[8:9], 1, v4
	v_cndmask_b32_e64 v4, 0, 1, s[40:41]
	v_cmp_ne_u32_e64 s[6:7], 1, v4
	s_add_i32 s89, s50, 2
	s_and_b32 s48, s89, s82
	s_lshr_b32 s84, s48, 2
	s_lshl_b32 s36, s48, 7
	s_lshl_b64 vcc, s[84:85], 9
	s_and_b32 s36, s36, 0x100
	s_add_u32 s49, s18, vcc_lo
	s_addc_u32 s51, s19, vcc_hi
	s_add_u32 s36, s49, s36
	s_mov_b32 s49, s85
	s_addc_u32 s51, s51, 0
	s_lshl_b64 s[48:49], s[48:49], 7
	s_add_u32 vcc_lo, s14, s48
	s_addc_u32 vcc_hi, s15, s49
	s_add_u32 s58, s16, s48
	s_addc_u32 s59, s17, s49
	s_cmp_eq_u32 s37, s50
	s_cselect_b32 s49, s43, s51
	s_cselect_b32 s48, s42, s36
	s_cselect_b32 s51, s97, s59
	s_cselect_b32 s50, s90, s58
	s_cselect_b32 vcc_hi, s45, vcc_hi
	s_cselect_b32 vcc_lo, s44, vcc_lo
	s_mov_b32 m0, s65
	v_lshl_add_u64 v[224:225], vcc, 0, v[216:217]
	v_lshl_add_u64 v[226:227], vcc, 0, v[220:221]
	s_add_u32 vcc_lo, vcc_lo, s10
	ds_read_b128 v[198:201], v251 offset:16384
	ds_read_b128 v[202:205], v251 offset:17408
	ds_read_b128 v[190:193], v251 offset:18432
	ds_read_b128 v[194:197], v251 offset:19456
	ds_read_b128 v[182:185], v251 offset:20480
	ds_read_b128 v[186:189], v251 offset:21504
	ds_read_b128 v[174:177], v251 offset:22528
	ds_read_b128 v[178:181], v251 offset:23552
	global_load_lds_dwordx4 v[224:225], off
	s_mov_b32 m0, s67
	s_addc_u32 vcc_hi, vcc_hi, s11
	global_load_lds_dwordx4 v[226:227], off
	v_lshl_add_u64 v[228:229], vcc, 0, v[216:217]
	s_mov_b32 m0, s68
	v_lshl_add_u64 v[230:231], vcc, 0, v[220:221]
	global_load_lds_dwordx4 v216, vcc
	s_mov_b32 m0, s69
	v_lshl_add_u64 v[232:233], s[48:49], 0, v[214:215]
	global_load_lds_dwordx4 v220, vcc
	s_mov_b32 m0, s64
	v_lshl_add_u64 v[234:235], s[48:49], 0, v[218:219]
	global_load_lds_dwordx4 v214, s[48:49]
	s_mov_b32 m0, s70
	v_lshl_add_u64 v[4:5], s[50:51], 0, v[222:223]
	global_load_lds_dwordx4 v218, s[48:49]
	s_and_saveexec_b64 s[50:51], s[2:3]
	s_cbranch_execz .LBB0_1228
	s_add_i32 s36, s57, 0
	s_add_i32 m0, s36, 0x22400
	s_nop 0
	global_load_lds_dwordx4 v[4:5], off

; #define PG8_LDX(b) do { if constexpr (XR) { _Pragma("unroll") for (int k = 0; k < 2; ++k) Ax_[k] = *(const PG8_LAS bf16x8*)(lds + XR_OFF + (b) * 2048 + aoffx + k * 1024); } } while (0)
; #define PG8_MMAX() do { if constexpr (XR) { if (hasx) { __builtin_amdgcn_s_setprio(1); if (wr == 0) PG8_MMAX_(B0); else PG8_MMAX_(B1); __builtin_amdgcn_s_setprio(0); } } } while (0)
; #define PG8_WAIT_LOOP() do { if constexpr (XR) PG8_WAIT_V(9); else PG8_WAIT_V(8); } while (0)
; #define PG8_STAGE(bufoff, gbase, voff) do { _Pragma("unroll") for (int _i = 0; _i < 2; ++_i) \
;         __builtin_amdgcn_global_load_lds((const unsigned*)((const char*)(gbase) + (voff)[_i]), (PG8_LAS unsigned*)(lds + (bufoff) + ldsw + _i * 8192), 16, 0, 0); } while (0)
; #define PG8_LDA(dst, b, h) do { _Pragma("unroll") for (int m = 0; m < 4; ++m) _Pragma("unroll") for (int k = 0; k < 2; ++k) dst[m][k] = *(const PG8_LAS bf16x8*)(lds + PG8_SA(b, h) + aoff + m * 2048 + k * 1024); } while (0)
; #define PG8_LDB(dst, b, h) do { _Pragma("unroll") for (int n = 0; n < 2; ++n) _Pragma("unroll") for (int k = 0; k < 2; ++k) dst[n][k] = *(const PG8_LAS bf16x8*)(lds + PG8_SB(b, h) + boff + n * 2048 + k * 1024); } while (0)
; #define PG8_MMA(ai, bj, At, Bt) do { __builtin_amdgcn_s_setprio(1); _Pragma("unroll") for (int m = 0; m < 4; ++m) _Pragma("unroll") for (int n = 0; n < 2; ++n) _Pragma("unroll") for (int k = 0; k < 2; ++k) \
;         acc[ai][bj][m][n] = __builtin_amdgcn_mfma_f32_16x16x32_bf16(Bt[n][k], At[m][k], acc[ai][bj][m][n], 0, 0, 0); __builtin_amdgcn_s_setprio(0); } while (0)
; #define PG8_WAIT_L(n) asm volatile("s_waitcnt lgkmcnt(" #n ")" ::: "memory")
; #define PG8_BAR __builtin_amdgcn_s_barrier()
; #define PG8_SCHED __builtin_amdgcn_sched_barrier(0)
; template <class Epi, class Sched, bool ALIGN_EPI = false, bool SP2 = false, bool DRAIN = true, bool XR = false>
; __device__ __forceinline__ void gemm_phase(PG8_LAS unsigned char* lds, const Gemm g, const Sched& S, const Epi& E) {
;     ...
;             PG8_LDB(B0, 0, 0); PG8_LDB(B1, 0, 1); PG8_SCHED; PG8_LDA(At, 0, 0); PG8_LDX(0); PG8_STAGE(PG8_SA(1, 1), a1 + hstepA, voffA);
;             PG8_WAIT_LOOP(); PG8_WAIT_L(0); PG8_BAR; PG8_MMA(0, 0, At, B0); PG8_MMA(0, 1, At, B1); PG8_MMAX(); PG8_BAR; PG8_SCHED;
.LBB0_1359:
	v_add_u32_e32 v2, 0x10000, v248
	s_add_i32 s4, s90, -2
	ds_read_b128 v[158:161], v2
	ds_read_b128 v[162:165], v2 offset:1024
	ds_read_b128 v[166:169], v2 offset:2048
	ds_read_b128 v[170:173], v2 offset:3072
	v_add_u32_e32 v2, 0x14000, v248
	s_and_b32 s6, s4, s73
	ds_read_b128 v[142:145], v2
	ds_read_b128 v[146:149], v2 offset:1024
	ds_read_b128 v[150:153], v2 offset:2048
	ds_read_b128 v[154:157], v2 offset:3072
	s_lshr_b32 s84, s6, 2
	s_lshl_b32 s6, s6, 7
	s_lshl_b64 s[4:5], s[84:85], 9
	s_and_b32 s6, s6, 0x100
	s_add_u32 s4, s56, s4
	s_addc_u32 s5, s57, s5
	s_add_u32 s4, s4, s6
	s_addc_u32 s5, s5, 0
	s_add_u32 s4, s4, s28
	s_addc_u32 s5, s5, s29
	v_lshl_add_u64 v[4:5], s[4:5], 0, v[220:221]
	v_add_u32_e32 v2, 0x22400, v250
	v_lshl_add_u64 v[4:5], v[4:5], 0, s[86:87]
	s_add_i32 m0, s13, 0xc000
	ds_read_b128 v[182:185], v249
	ds_read_b128 v[186:189], v249 offset:1024
	ds_read_b128 v[190:193], v249 offset:2048
	ds_read_b128 v[194:197], v249 offset:3072
	ds_read_b128 v[198:201], v249 offset:4096
	ds_read_b128 v[202:205], v249 offset:5120
	ds_read_b128 v[206:209], v249 offset:6144
	ds_read_b128 v[224:227], v249 offset:7168
	ds_read_b128 v[174:177], v2
	ds_read_b128 v[178:181], v2 offset:1024
	global_load_lds_dwordx4 v[4:5], off
	v_lshl_add_u64 v[4:5], s[4:5], 0, v[216:217]
	v_lshl_add_u64 v[4:5], v[4:5], 0, s[86:87]
	s_add_i32 m0, s13, 0xe000
	s_nop 0
	global_load_lds_dwordx4 v[4:5], off
	s_waitcnt vmcnt(9)
	s_waitcnt lgkmcnt(0)
	s_barrier
	v_mfma_f32_16x16x32_bf16 v[138:141], v[158:161], v[182:185], v[138:141]
	v_mfma_f32_16x16x32_bf16 v[134:137], v[166:169], v[182:185], v[134:137]
	v_mfma_f32_16x16x32_bf16 v[122:125], v[158:161], v[190:193], v[122:125]
	v_mfma_f32_16x16x32_bf16 v[118:121], v[166:169], v[190:193], v[118:121]
	v_mfma_f32_16x16x32_bf16 v[106:109], v[158:161], v[198:201], v[106:109]
	v_mfma_f32_16x16x32_bf16 v[102:105], v[166:169], v[198:201], v[102:105]
	v_mfma_f32_16x16x32_bf16 v[90:93], v[158:161], v[206:209], v[90:93]
	v_mfma_f32_16x16x32_bf16 v[86:89], v[166:169], v[206:209], v[86:89]
	v_mfma_f32_16x16x32_bf16 v[138:141], v[162:165], v[186:189], v[138:141]
	v_mfma_f32_16x16x32_bf16 v[134:137], v[170:173], v[186:189], v[134:137]
	v_mfma_f32_16x16x32_bf16 v[122:125], v[162:165], v[194:197], v[122:125]
	v_mfma_f32_16x16x32_bf16 v[118:121], v[170:173], v[194:197], v[118:121]
	v_mfma_f32_16x16x32_bf16 v[106:109], v[162:165], v[202:205], v[106:109]
	v_mfma_f32_16x16x32_bf16 v[102:105], v[170:173], v[202:205], v[102:105]
	v_mfma_f32_16x16x32_bf16 v[90:93], v[162:165], v[224:227], v[90:93]
	v_mfma_f32_16x16x32_bf16 v[86:89], v[170:173], v[224:227], v[86:89]
	v_mfma_f32_16x16x32_bf16 v[130:133], v[142:145], v[182:185], v[130:133]
	v_mfma_f32_16x16x32_bf16 v[126:129], v[150:153], v[182:185], v[126:129]
	v_mfma_f32_16x16x32_bf16 v[114:117], v[142:145], v[190:193], v[114:117]
	v_mfma_f32_16x16x32_bf16 v[110:113], v[150:153], v[190:193], v[110:113]
	v_mfma_f32_16x16x32_bf16 v[98:101], v[142:145], v[198:201], v[98:101]
	v_mfma_f32_16x16x32_bf16 v[94:97], v[150:153], v[198:201], v[94:97]
	v_mfma_f32_16x16x32_bf16 v[82:85], v[142:145], v[206:209], v[82:85]
	v_mfma_f32_16x16x32_bf16 v[78:81], v[150:153], v[206:209], v[78:81]
	v_mfma_f32_16x16x32_bf16 v[130:133], v[146:149], v[186:189], v[130:133]
	v_mfma_f32_16x16x32_bf16 v[126:129], v[154:157], v[186:189], v[126:129]
	v_mfma_f32_16x16x32_bf16 v[114:117], v[146:149], v[194:197], v[114:117]
	v_mfma_f32_16x16x32_bf16 v[110:113], v[154:157], v[194:197], v[110:113]
	v_mfma_f32_16x16x32_bf16 v[98:101], v[146:149], v[202:205], v[98:101]
	v_mfma_f32_16x16x32_bf16 v[94:97], v[154:157], v[202:205], v[94:97]
	v_mfma_f32_16x16x32_bf16 v[82:85], v[146:149], v[224:227], v[82:85]
	v_mfma_f32_16x16x32_bf16 v[78:81], v[154:157], v[224:227], v[78:81]
	s_cmp_eq_u64 s[46:47], 0
	s_cbranch_scc1 .LBB0_1365
	s_mov_b64 s[60:61], -1
	s_cmp_eq_u64 s[44:45], 0
	s_cbranch_scc1 .LBB0_1362
	v_mfma_f32_16x16x32_bf16 v[10:13], v[142:145], v[174:177], v[10:13]
	s_mov_b64 s[60:61], 0
	v_mfma_f32_16x16x32_bf16 v[6:9], v[150:153], v[174:177], v[6:9]
	v_mfma_f32_16x16x32_bf16 v[10:13], v[146:149], v[178:181], v[10:13]
	v_mfma_f32_16x16x32_bf16 v[6:9], v[154:157], v[178:181], v[6:9]

; #define PG8_STAGEX(b, gbase) do { if constexpr (XR) { if (lane < 16) __builtin_amdgcn_global_load_lds((const unsigned*)((const char*)(gbase) + voffX), (PG8_LAS unsigned*)(lds + XR_OFF + (b) * 2048 + wid * 256), 16, 0, 0); } } while (0)
; #define PG8_MMAX() do { if constexpr (XR) { if (hasx) { __builtin_amdgcn_s_setprio(1); if (wr == 0) PG8_MMAX_(B0); else PG8_MMAX_(B1); __builtin_amdgcn_s_setprio(0); } } } while (0)
; #define PG8_WAIT_LOOP() do { if constexpr (XR) PG8_WAIT_V(9); else PG8_WAIT_V(8); } while (0)
; #define PG8_STAGE(bufoff, gbase, voff) do { _Pragma("unroll") for (int _i = 0; _i < 2; ++_i) \
;         __builtin_amdgcn_global_load_lds((const unsigned*)((const char*)(gbase) + (voff)[_i]), (PG8_LAS unsigned*)(lds + (bufoff) + ldsw + _i * 8192), 16, 0, 0); } while (0)
; #define PG8_LDA(dst, b, h) do { _Pragma("unroll") for (int m = 0; m < 4; ++m) _Pragma("unroll") for (int k = 0; k < 2; ++k) dst[m][k] = *(const PG8_LAS bf16x8*)(lds + PG8_SA(b, h) + aoff + m * 2048 + k * 1024); } while (0)
; #define PG8_MMA(ai, bj, At, Bt) do { __builtin_amdgcn_s_setprio(1); _Pragma("unroll") for (int m = 0; m < 4; ++m) _Pragma("unroll") for (int n = 0; n < 2; ++n) _Pragma("unroll") for (int k = 0; k < 2; ++k) \
;         acc[ai][bj][m][n] = __builtin_amdgcn_mfma_f32_16x16x32_bf16(Bt[n][k], At[m][k], acc[ai][bj][m][n], 0, 0, 0); __builtin_amdgcn_s_setprio(0); } while (0)
; #define PG8_WAIT_L(n) asm volatile("s_waitcnt lgkmcnt(" #n ")" ::: "memory")
; #define PG8_BAR __builtin_amdgcn_s_barrier()
; template <class Epi, class Sched, bool ALIGN_EPI = false, bool SP2 = false, bool DRAIN = true, bool XR = false>
; __device__ __forceinline__ void gemm_phase(PG8_LAS unsigned char* lds, const Gemm g, const Sched& S, const Epi& E) {
;     ...
;             const char* a1 = cA + PG8_KOA(t) + kstep;
;             const char* a2 = last ? nA + ka0 : cA + PG8_KOA(t + 2); const char* b2 = last ? nB + kb0 : cB + PG8_KOB(t + 2);
;             const char* x2 = XR ? (last ? nX + kx0 : cX + PG8_KOX(t + 2)) : nullptr; const char* x3 = XR ? x2 + kstep : nullptr;
;     ...
;             PG8_WAIT_LOOP(); PG8_WAIT_L(0); PG8_BAR; PG8_MMA(0, 0, At, B0); PG8_MMA(0, 1, At, B1); PG8_MMAX(); PG8_BAR; PG8_SCHED;
;             PG8_LDA(At, 0, 1); PG8_STAGE(PG8_SB(0, 0), b2, voffB); PG8_STAGE(PG8_SB(0, 1), b2 + hstep, voffB); PG8_STAGE(PG8_SA(0, 0), a2, voffA); PG8_STAGEX(0, x2);
.LBB0_1364:
.LBB0_1365:
	s_barrier
	v_cndmask_b32_e64 v2, 0, 1, s[46:47]
	v_cmp_ne_u32_e64 s[6:7], 1, v2
	v_cndmask_b32_e64 v2, 0, 1, s[44:45]
	v_cmp_ne_u32_e64 s[4:5], 1, v2
	s_and_b32 s8, s90, s73
	s_lshr_b32 s84, s8, 2
	s_lshl_b32 s9, s8, 7
	s_lshl_b64 s[20:21], s[84:85], 9
	s_and_b32 s9, s9, 0x100
	s_add_u32 s20, s56, s20
	s_addc_u32 s21, s57, s21
	s_add_u32 s20, s20, s9
	s_mov_b32 s9, s85
	s_addc_u32 s21, s21, 0
	s_lshl_b64 s[8:9], s[8:9], 7
	s_add_u32 s36, s54, s8
	s_addc_u32 s62, s55, s9
	s_add_u32 s8, s58, s8
	s_addc_u32 s9, s59, s9
	s_cmp_eq_u32 s65, s90
	s_cselect_b32 s61, s49, s21
	s_cselect_b32 s60, s48, s20
	s_cselect_b32 s9, s88, s9
	s_cselect_b32 s8, s89, s8
	s_cselect_b32 s21, s51, s62
	s_cselect_b32 s20, s50, s36
	s_mov_b32 m0, s14
	v_lshl_add_u64 v[224:225], s[20:21], 0, v[218:219]
	v_lshl_add_u64 v[226:227], s[20:21], 0, v[214:215]
	s_add_u32 s20, s20, s28
	ds_read_b128 v[198:201], v249 offset:16384
	ds_read_b128 v[202:205], v249 offset:17408
	ds_read_b128 v[190:193], v249 offset:18432
	ds_read_b128 v[194:197], v249 offset:19456
	ds_read_b128 v[182:185], v249 offset:20480
	ds_read_b128 v[186:189], v249 offset:21504
	ds_read_b128 v[174:177], v249 offset:22528
	ds_read_b128 v[178:181], v249 offset:23552
	global_load_lds_dwordx4 v[224:225], off
	s_mov_b32 m0, s15
	s_addc_u32 s21, s21, s29
	global_load_lds_dwordx4 v[226:227], off
	v_lshl_add_u64 v[228:229], s[20:21], 0, v[218:219]
	s_mov_b32 m0, s16
	v_lshl_add_u64 v[230:231], s[20:21], 0, v[214:215]
	global_load_lds_dwordx4 v218, s[20:21]
	s_mov_b32 m0, s17
	v_lshl_add_u64 v[232:233], s[60:61], 0, v[220:221]
	global_load_lds_dwordx4 v214, s[20:21]
	s_mov_b32 m0, s13
	v_lshl_add_u64 v[234:235], s[60:61], 0, v[216:217]
	global_load_lds_dwordx4 v220, s[60:61]
	s_mov_b32 m0, s18
	v_lshl_add_u64 v[4:5], s[8:9], 0, v[222:223]
	global_load_lds_dwordx4 v216, s[60:61]
	s_and_saveexec_b64 s[62:63], s[0:1]
	s_cbranch_execz .LBB0_1367
	s_add_i32 s8, s12, 0
	s_add_i32 m0, s8, 0x22400
	s_nop 0
	global_load_lds_dwordx4 v[4:5], off

; #define PG8_LDX(b) do { if constexpr (XR) { _Pragma("unroll") for (int k = 0; k < 2; ++k) Ax_[k] = *(const PG8_LAS bf16x8*)(lds + XR_OFF + (b) * 2048 + aoffx + k * 1024); } } while (0)
; #define PG8_MMAX() do { if constexpr (XR) { if (hasx) { __builtin_amdgcn_s_setprio(1); if (wr == 0) PG8_MMAX_(B0); else PG8_MMAX_(B1); __builtin_amdgcn_s_setprio(0); } } } while (0)
; #define PG8_WAIT_LOOP() do { if constexpr (XR) PG8_WAIT_V(9); else PG8_WAIT_V(8); } while (0)
; #define PG8_STAGE(bufoff, gbase, voff) do { _Pragma("unroll") for (int _i = 0; _i < 2; ++_i) \
;         __builtin_amdgcn_global_load_lds((const unsigned*)((const char*)(gbase) + (voff)[_i]), (PG8_LAS unsigned*)(lds + (bufoff) + ldsw + _i * 8192), 16, 0, 0); } while (0)
; #define PG8_LDA(dst, b, h) do { _Pragma("unroll") for (int m = 0; m < 4; ++m) _Pragma("unroll") for (int k = 0; k < 2; ++k) dst[m][k] = *(const PG8_LAS bf16x8*)(lds + PG8_SA(b, h) + aoff + m * 2048 + k * 1024); } while (0)
; #define PG8_LDB(dst, b, h) do { _Pragma("unroll") for (int n = 0; n < 2; ++n) _Pragma("unroll") for (int k = 0; k < 2; ++k) dst[n][k] = *(const PG8_LAS bf16x8*)(lds + PG8_SB(b, h) + boff + n * 2048 + k * 1024); } while (0)
; #define PG8_MMA(ai, bj, At, Bt) do { __builtin_amdgcn_s_setprio(1); _Pragma("unroll") for (int m = 0; m < 4; ++m) _Pragma("unroll") for (int n = 0; n < 2; ++n) _Pragma("unroll") for (int k = 0; k < 2; ++k) \
;         acc[ai][bj][m][n] = __builtin_amdgcn_mfma_f32_16x16x32_bf16(Bt[n][k], At[m][k], acc[ai][bj][m][n], 0, 0, 0); __builtin_amdgcn_s_setprio(0); } while (0)
; #define PG8_WAIT_L(n) asm volatile("s_waitcnt lgkmcnt(" #n ")" ::: "memory")
; #define PG8_BAR __builtin_amdgcn_s_barrier()
; #define PG8_SCHED __builtin_amdgcn_sched_barrier(0)
; template <class Epi, class Sched, bool ALIGN_EPI = false, bool SP2 = false, bool DRAIN = true, bool XR = false>
; __device__ __forceinline__ void gemm_phase(PG8_LAS unsigned char* lds, const Gemm g, const Sched& S, const Epi& E) {
;     ...
;             PG8_LDB(B0, 0, 0); PG8_LDB(B1, 0, 1); PG8_SCHED; PG8_LDA(At, 0, 0); PG8_LDX(0); PG8_STAGE(PG8_SA(1, 1), a1 + hstepA, voffA);
;             PG8_WAIT_LOOP(); PG8_WAIT_L(0); PG8_BAR; PG8_MMA(0, 0, At, B0); PG8_MMA(0, 1, At, B1); PG8_MMAX(); PG8_BAR; PG8_SCHED;
.LBB0_1501:
	s_add_i32 s64, s83, s70
	v_add_u32_e32 v140, 0x10000, v248
	v_add_u32_e32 v152, 0x14000, v248
	s_and_b32 s6, s64, s97
	ds_read_b128 v[156:159], v140
	ds_read_b128 v[160:163], v140 offset:1024
	ds_read_b128 v[164:167], v140 offset:2048
	ds_read_b128 v[168:171], v140 offset:3072
	ds_read_b128 v[140:143], v152
	ds_read_b128 v[144:147], v152 offset:1024
	ds_read_b128 v[148:151], v152 offset:2048
	ds_read_b128 v[152:155], v152 offset:3072
	s_lshr_b32 s84, s6, 2
	s_lshl_b32 s6, s6, 7
	s_lshl_b64 s[4:5], s[84:85], 9
	s_and_b32 s6, s6, 0x100
	s_add_u32 s4, s40, s4
	s_addc_u32 s5, s41, s5
	s_add_u32 s4, s4, s6
	s_addc_u32 s5, s5, 0
	s_add_u32 s4, s4, s28
	s_addc_u32 s5, s5, s29
	v_lshl_add_u64 v[212:213], s[4:5], 0, v[204:205]
	v_add_u32_e32 v176, 0x22400, v250
	v_lshl_add_u64 v[212:213], v[212:213], 0, s[86:87]
	s_add_i32 m0, s90, 0xc000
	ds_read_b128 v[180:183], v249
	ds_read_b128 v[184:187], v249 offset:1024
	ds_read_b128 v[188:191], v249 offset:2048
	ds_read_b128 v[192:195], v249 offset:3072
	ds_read_b128 v[196:199], v249 offset:4096
	ds_read_b128 v[200:203], v249 offset:5120
	ds_read_b128 v[206:209], v249 offset:6144
	ds_read_b128 v[222:225], v249 offset:7168
	ds_read_b128 v[172:175], v176
	ds_read_b128 v[176:179], v176 offset:1024
	global_load_lds_dwordx4 v[212:213], off
	v_lshl_add_u64 v[212:213], s[4:5], 0, v[216:217]
	v_lshl_add_u64 v[212:213], v[212:213], 0, s[86:87]
	s_add_i32 m0, s90, 0xe000
	s_nop 0
	global_load_lds_dwordx4 v[212:213], off
	s_waitcnt vmcnt(9)
	s_waitcnt lgkmcnt(0)
	s_barrier
	v_mfma_f32_16x16x32_bf16 v[136:139], v[156:159], v[180:183], v[136:139]
	v_mfma_f32_16x16x32_bf16 v[132:135], v[164:167], v[180:183], v[132:135]
	v_mfma_f32_16x16x32_bf16 v[128:131], v[156:159], v[188:191], v[128:131]
	v_mfma_f32_16x16x32_bf16 v[124:127], v[164:167], v[188:191], v[124:127]
	v_mfma_f32_16x16x32_bf16 v[120:123], v[156:159], v[196:199], v[120:123]
	v_mfma_f32_16x16x32_bf16 v[116:119], v[164:167], v[196:199], v[116:119]
	v_mfma_f32_16x16x32_bf16 v[112:115], v[156:159], v[206:209], v[112:115]
	v_mfma_f32_16x16x32_bf16 v[108:111], v[164:167], v[206:209], v[108:111]
	v_mfma_f32_16x16x32_bf16 v[136:139], v[160:163], v[184:187], v[136:139]
	v_mfma_f32_16x16x32_bf16 v[132:135], v[168:171], v[184:187], v[132:135]
	v_mfma_f32_16x16x32_bf16 v[128:131], v[160:163], v[192:195], v[128:131]
	v_mfma_f32_16x16x32_bf16 v[124:127], v[168:171], v[192:195], v[124:127]
	v_mfma_f32_16x16x32_bf16 v[120:123], v[160:163], v[200:203], v[120:123]
	v_mfma_f32_16x16x32_bf16 v[116:119], v[168:171], v[200:203], v[116:119]
	v_mfma_f32_16x16x32_bf16 v[112:115], v[160:163], v[222:225], v[112:115]
	v_mfma_f32_16x16x32_bf16 v[108:111], v[168:171], v[222:225], v[108:111]
	v_mfma_f32_16x16x32_bf16 v[104:107], v[140:143], v[180:183], v[104:107]
	v_mfma_f32_16x16x32_bf16 v[100:103], v[148:151], v[180:183], v[100:103]
	v_mfma_f32_16x16x32_bf16 v[96:99], v[140:143], v[188:191], v[96:99]
	v_mfma_f32_16x16x32_bf16 v[92:95], v[148:151], v[188:191], v[92:95]
	v_mfma_f32_16x16x32_bf16 v[88:91], v[140:143], v[196:199], v[88:91]
	v_mfma_f32_16x16x32_bf16 v[84:87], v[148:151], v[196:199], v[84:87]
	v_mfma_f32_16x16x32_bf16 v[80:83], v[140:143], v[206:209], v[80:83]
	v_mfma_f32_16x16x32_bf16 v[76:79], v[148:151], v[206:209], v[76:79]
	v_mfma_f32_16x16x32_bf16 v[104:107], v[144:147], v[184:187], v[104:107]
	v_mfma_f32_16x16x32_bf16 v[100:103], v[152:155], v[184:187], v[100:103]
	v_mfma_f32_16x16x32_bf16 v[96:99], v[144:147], v[192:195], v[96:99]
	v_mfma_f32_16x16x32_bf16 v[92:95], v[152:155], v[192:195], v[92:95]
	v_mfma_f32_16x16x32_bf16 v[88:91], v[144:147], v[200:203], v[88:91]
	v_mfma_f32_16x16x32_bf16 v[84:87], v[152:155], v[200:203], v[84:87]
	v_mfma_f32_16x16x32_bf16 v[80:83], v[144:147], v[222:225], v[80:83]
	v_mfma_f32_16x16x32_bf16 v[76:79], v[152:155], v[222:225], v[76:79]
	s_cmp_eq_u64 s[46:47], 0
	s_cbranch_scc1 .LBB0_1507
	s_mov_b64 s[62:63], -1
	s_cmp_eq_u64 s[52:53], 0
	s_cbranch_scc1 .LBB0_1504
	v_mfma_f32_16x16x32_bf16 v[8:11], v[140:143], v[172:175], v[8:11]
	s_mov_b64 s[62:63], 0
	v_mfma_f32_16x16x32_bf16 v[4:7], v[148:151], v[172:175], v[4:7]
	v_mfma_f32_16x16x32_bf16 v[8:11], v[144:147], v[176:179], v[8:11]
	v_mfma_f32_16x16x32_bf16 v[4:7], v[152:155], v[176:179], v[4:7]

; #define PG8_STAGEX(b, gbase) do { if constexpr (XR) { if (lane < 16) __builtin_amdgcn_global_load_lds((const unsigned*)((const char*)(gbase) + voffX), (PG8_LAS unsigned*)(lds + XR_OFF + (b) * 2048 + wid * 256), 16, 0, 0); } } while (0)
; #define PG8_MMAX() do { if constexpr (XR) { if (hasx) { __builtin_amdgcn_s_setprio(1); if (wr == 0) PG8_MMAX_(B0); else PG8_MMAX_(B1); __builtin_amdgcn_s_setprio(0); } } } while (0)
; #define PG8_WAIT_LOOP() do { if constexpr (XR) PG8_WAIT_V(9); else PG8_WAIT_V(8); } while (0)
; #define PG8_STAGE(bufoff, gbase, voff) do { _Pragma("unroll") for (int _i = 0; _i < 2; ++_i) \
;         __builtin_amdgcn_global_load_lds((const unsigned*)((const char*)(gbase) + (voff)[_i]), (PG8_LAS unsigned*)(lds + (bufoff) + ldsw + _i * 8192), 16, 0, 0); } while (0)
; #define PG8_LDA(dst, b, h) do { _Pragma("unroll") for (int m = 0; m < 4; ++m) _Pragma("unroll") for (int k = 0; k < 2; ++k) dst[m][k] = *(const PG8_LAS bf16x8*)(lds + PG8_SA(b, h) + aoff + m * 2048 + k * 1024); } while (0)
; #define PG8_MMA(ai, bj, At, Bt) do { __builtin_amdgcn_s_setprio(1); _Pragma("unroll") for (int m = 0; m < 4; ++m) _Pragma("unroll") for (int n = 0; n < 2; ++n) _Pragma("unroll") for (int k = 0; k < 2; ++k) \
;         acc[ai][bj][m][n] = __builtin_amdgcn_mfma_f32_16x16x32_bf16(Bt[n][k], At[m][k], acc[ai][bj][m][n], 0, 0, 0); __builtin_amdgcn_s_setprio(0); } while (0)
; #define PG8_WAIT_L(n) asm volatile("s_waitcnt lgkmcnt(" #n ")" ::: "memory")
; #define PG8_BAR __builtin_amdgcn_s_barrier()
; template <class Epi, class Sched, bool ALIGN_EPI = false, bool SP2 = false, bool DRAIN = true, bool XR = false>
; __device__ __forceinline__ void gemm_phase(PG8_LAS unsigned char* lds, const Gemm g, const Sched& S, const Epi& E) {
;     ...
;             const char* a1 = cA + PG8_KOA(t) + kstep;
;             const char* a2 = last ? nA + ka0 : cA + PG8_KOA(t + 2); const char* b2 = last ? nB + kb0 : cB + PG8_KOB(t + 2);
;             const char* x2 = XR ? (last ? nX + kx0 : cX + PG8_KOX(t + 2)) : nullptr; const char* x3 = XR ? x2 + kstep : nullptr;
;     ...
;             PG8_WAIT_LOOP(); PG8_WAIT_L(0); PG8_BAR; PG8_MMA(0, 0, At, B0); PG8_MMA(0, 1, At, B1); PG8_MMAX(); PG8_BAR; PG8_SCHED;
;             PG8_LDA(At, 0, 1); PG8_STAGE(PG8_SB(0, 0), b2, voffB); PG8_STAGE(PG8_SB(0, 1), b2 + hstep, voffB); PG8_STAGE(PG8_SA(0, 0), a2, voffA); PG8_STAGEX(0, x2);
.LBB0_1506:
.LBB0_1507:
	s_barrier
	v_cndmask_b32_e64 v180, 0, 1, s[46:47]
	v_cmp_ne_u32_e64 s[6:7], 1, v180
	v_cndmask_b32_e64 v180, 0, 1, s[52:53]
	v_cmp_ne_u32_e64 s[4:5], 1, v180
	s_add_i32 s64, s64, 2
	s_and_b32 s62, s64, s97
	s_lshr_b32 s84, s62, 2
	s_lshl_b32 s36, s62, 7
	s_lshl_b64 s[64:65], s[84:85], 9
	s_and_b32 s36, s36, 0x100
	s_add_u32 s63, s40, s64
	s_addc_u32 s64, s41, s65
	s_add_u32 s36, s63, s36
	s_mov_b32 s63, s85
	s_addc_u32 s64, s64, 0
	s_lshl_b64 s[62:63], s[62:63], 7
	s_add_u32 vcc_lo, s34, s62
	s_addc_u32 vcc_hi, s35, s63
	s_add_u32 s81, s42, s62
	s_addc_u32 s65, s43, s63
	s_cmp_eq_u32 s91, s70
	s_cselect_b32 s63, s8, s64
	s_cselect_b32 s62, s78, s36
	s_cselect_b32 s65, s69, s65
	s_cselect_b32 s64, s21, s81
	s_cselect_b32 vcc_hi, s20, vcc_hi
	s_cselect_b32 vcc_lo, s9, vcc_lo
	s_mov_b32 m0, s16
	v_lshl_add_u64 v[224:225], vcc, 0, v[214:215]
	v_lshl_add_u64 v[226:227], vcc, 0, v[218:219]
	s_add_u32 vcc_lo, vcc_lo, s28
	ds_read_b128 v[196:199], v249 offset:16384
	ds_read_b128 v[200:203], v249 offset:17408
	ds_read_b128 v[188:191], v249 offset:18432
	ds_read_b128 v[192:195], v249 offset:19456
	ds_read_b128 v[180:183], v249 offset:20480
	ds_read_b128 v[184:187], v249 offset:21504
	ds_read_b128 v[172:175], v249 offset:22528
	ds_read_b128 v[176:179], v249 offset:23552
	global_load_lds_dwordx4 v[224:225], off
	s_mov_b32 m0, s17
	s_addc_u32 vcc_hi, vcc_hi, s29
	global_load_lds_dwordx4 v[226:227], off
	v_lshl_add_u64 v[228:229], vcc, 0, v[214:215]
	s_mov_b32 m0, s93
	v_lshl_add_u64 v[230:231], vcc, 0, v[218:219]
	global_load_lds_dwordx4 v214, vcc
	s_mov_b32 m0, s24
	v_lshl_add_u64 v[232:233], s[62:63], 0, v[204:205]
	global_load_lds_dwordx4 v218, vcc
	s_mov_b32 m0, s90
	v_lshl_add_u64 v[234:235], s[62:63], 0, v[216:217]
	global_load_lds_dwordx4 v204, s[62:63]
	s_mov_b32 m0, s25
	v_lshl_add_u64 v[222:223], s[64:65], 0, v[220:221]
	global_load_lds_dwordx4 v216, s[62:63]
	s_and_saveexec_b64 s[64:65], s[2:3]
	s_cbranch_execz .LBB0_1509
	s_add_i32 s36, s26, 0
	s_add_i32 m0, s36, 0x22400
	s_nop 0
	global_load_lds_dwordx4 v[222:223], off

; #define PG8_LDX(b) do { if constexpr (XR) { _Pragma("unroll") for (int k = 0; k < 2; ++k) Ax_[k] = *(const PG8_LAS bf16x8*)(lds + XR_OFF + (b) * 2048 + aoffx + k * 1024); } } while (0)
; #define PG8_MMAX() do { if constexpr (XR) { if (hasx) { __builtin_amdgcn_s_setprio(1); if (wr == 0) PG8_MMAX_(B0); else PG8_MMAX_(B1); __builtin_amdgcn_s_setprio(0); } } } while (0)
; #define PG8_WAIT_LOOP() do { if constexpr (XR) PG8_WAIT_V(9); else PG8_WAIT_V(8); } while (0)
; #define PG8_STAGE(bufoff, gbase, voff) do { _Pragma("unroll") for (int _i = 0; _i < 2; ++_i) \
;         __builtin_amdgcn_global_load_lds((const unsigned*)((const char*)(gbase) + (voff)[_i]), (PG8_LAS unsigned*)(lds + (bufoff) + ldsw + _i * 8192), 16, 0, 0); } while (0)
; #define PG8_LDA(dst, b, h) do { _Pragma("unroll") for (int m = 0; m < 4; ++m) _Pragma("unroll") for (int k = 0; k < 2; ++k) dst[m][k] = *(const PG8_LAS bf16x8*)(lds + PG8_SA(b, h) + aoff + m * 2048 + k * 1024); } while (0)
; #define PG8_LDB(dst, b, h) do { _Pragma("unroll") for (int n = 0; n < 2; ++n) _Pragma("unroll") for (int k = 0; k < 2; ++k) dst[n][k] = *(const PG8_LAS bf16x8*)(lds + PG8_SB(b, h) + boff + n * 2048 + k * 1024); } while (0)
; #define PG8_MMA(ai, bj, At, Bt) do { __builtin_amdgcn_s_setprio(1); _Pragma("unroll") for (int m = 0; m < 4; ++m) _Pragma("unroll") for (int n = 0; n < 2; ++n) _Pragma("unroll") for (int k = 0; k < 2; ++k) \
;         acc[ai][bj][m][n] = __builtin_amdgcn_mfma_f32_16x16x32_bf16(Bt[n][k], At[m][k], acc[ai][bj][m][n], 0, 0, 0); __builtin_amdgcn_s_setprio(0); } while (0)
; #define PG8_WAIT_L(n) asm volatile("s_waitcnt lgkmcnt(" #n ")" ::: "memory")
; #define PG8_BAR __builtin_amdgcn_s_barrier()
; #define PG8_SCHED __builtin_amdgcn_sched_barrier(0)
; template <class Epi, class Sched, bool ALIGN_EPI = false, bool SP2 = false, bool DRAIN = true, bool XR = false>
; __device__ __forceinline__ void gemm_phase(PG8_LAS unsigned char* lds, const Gemm g, const Sched& S, const Epi& E) {
;     ...
;             PG8_LDB(B0, 0, 0); PG8_LDB(B1, 0, 1); PG8_SCHED; PG8_LDA(At, 0, 0); PG8_LDX(0); PG8_STAGE(PG8_SA(1, 1), a1 + hstepA, voffA);
;             PG8_WAIT_LOOP(); PG8_WAIT_L(0); PG8_BAR; PG8_MMA(0, 0, At, B0); PG8_MMA(0, 1, At, B1); PG8_MMAX(); PG8_BAR; PG8_SCHED;
.LBB0_1652:
	v_add_u32_e32 v2, 0x10000, v248
	s_add_i32 s46, s54, s89
	ds_read_b128 v[158:161], v2
	ds_read_b128 v[162:165], v2 offset:1024
	ds_read_b128 v[166:169], v2 offset:2048
	ds_read_b128 v[170:173], v2 offset:3072
	v_add_u32_e32 v2, 0x14000, v248
	s_and_b32 s6, s46, s59
	ds_read_b128 v[142:145], v2
	ds_read_b128 v[146:149], v2 offset:1024
	ds_read_b128 v[150:153], v2 offset:2048
	ds_read_b128 v[154:157], v2 offset:3072
	s_lshr_b32 s84, s6, 2
	s_lshl_b32 s6, s6, 7
	s_lshl_b64 s[0:1], s[84:85], 17
	s_and_b32 s6, s6, 0x100
	s_add_u32 s0, s40, s0
	s_addc_u32 s1, s41, s1
	s_add_u32 s0, s0, s6
	s_addc_u32 s1, s1, 0
	s_add_u32 s0, s0, 0x10080
	s_addc_u32 s1, s1, 0
	v_add_u32_e32 v2, 0x22400, v250
	s_add_i32 m0, s63, 0xc000
	ds_read_b128 v[182:185], v249
	ds_read_b128 v[186:189], v249 offset:1024
	ds_read_b128 v[190:193], v249 offset:2048
	ds_read_b128 v[194:197], v249 offset:3072
	ds_read_b128 v[198:201], v249 offset:4096
	ds_read_b128 v[202:205], v249 offset:5120
	ds_read_b128 v[206:209], v249 offset:6144
	ds_read_b128 v[224:227], v249 offset:7168
	ds_read_b128 v[174:177], v2
	ds_read_b128 v[178:181], v2 offset:1024
	global_load_lds_dwordx4 v214, s[0:1]
	s_add_i32 m0, s63, 0xe000
	s_nop 0
	global_load_lds_dwordx4 v218, s[0:1]
	s_waitcnt vmcnt(9)
	s_waitcnt lgkmcnt(0)
	s_barrier
	v_mfma_f32_16x16x32_bf16 v[138:141], v[158:161], v[182:185], v[138:141]
	v_mfma_f32_16x16x32_bf16 v[134:137], v[166:169], v[182:185], v[134:137]
	v_mfma_f32_16x16x32_bf16 v[122:125], v[158:161], v[190:193], v[122:125]
	v_mfma_f32_16x16x32_bf16 v[118:121], v[166:169], v[190:193], v[118:121]
	v_mfma_f32_16x16x32_bf16 v[106:109], v[158:161], v[198:201], v[106:109]
	v_mfma_f32_16x16x32_bf16 v[102:105], v[166:169], v[198:201], v[102:105]
	v_mfma_f32_16x16x32_bf16 v[90:93], v[158:161], v[206:209], v[90:93]
	v_mfma_f32_16x16x32_bf16 v[86:89], v[166:169], v[206:209], v[86:89]
	v_mfma_f32_16x16x32_bf16 v[138:141], v[162:165], v[186:189], v[138:141]
	v_mfma_f32_16x16x32_bf16 v[134:137], v[170:173], v[186:189], v[134:137]
	v_mfma_f32_16x16x32_bf16 v[122:125], v[162:165], v[194:197], v[122:125]
	v_mfma_f32_16x16x32_bf16 v[118:121], v[170:173], v[194:197], v[118:121]
	v_mfma_f32_16x16x32_bf16 v[106:109], v[162:165], v[202:205], v[106:109]
	v_mfma_f32_16x16x32_bf16 v[102:105], v[170:173], v[202:205], v[102:105]
	v_mfma_f32_16x16x32_bf16 v[90:93], v[162:165], v[224:227], v[90:93]
	v_mfma_f32_16x16x32_bf16 v[86:89], v[170:173], v[224:227], v[86:89]
	v_mfma_f32_16x16x32_bf16 v[130:133], v[142:145], v[182:185], v[130:133]
	v_mfma_f32_16x16x32_bf16 v[126:129], v[150:153], v[182:185], v[126:129]
	v_mfma_f32_16x16x32_bf16 v[114:117], v[142:145], v[190:193], v[114:117]
	v_mfma_f32_16x16x32_bf16 v[110:113], v[150:153], v[190:193], v[110:113]
	v_mfma_f32_16x16x32_bf16 v[98:101], v[142:145], v[198:201], v[98:101]
	v_mfma_f32_16x16x32_bf16 v[94:97], v[150:153], v[198:201], v[94:97]
	v_mfma_f32_16x16x32_bf16 v[82:85], v[142:145], v[206:209], v[82:85]
	v_mfma_f32_16x16x32_bf16 v[78:81], v[150:153], v[206:209], v[78:81]
	v_mfma_f32_16x16x32_bf16 v[130:133], v[146:149], v[186:189], v[130:133]
	v_mfma_f32_16x16x32_bf16 v[126:129], v[154:157], v[186:189], v[126:129]
	v_mfma_f32_16x16x32_bf16 v[114:117], v[146:149], v[194:197], v[114:117]
	v_mfma_f32_16x16x32_bf16 v[110:113], v[154:157], v[194:197], v[110:113]
	v_mfma_f32_16x16x32_bf16 v[98:101], v[146:149], v[202:205], v[98:101]
	v_mfma_f32_16x16x32_bf16 v[94:97], v[154:157], v[202:205], v[94:97]
	v_mfma_f32_16x16x32_bf16 v[82:85], v[146:149], v[224:227], v[82:85]
	v_mfma_f32_16x16x32_bf16 v[78:81], v[154:157], v[224:227], v[78:81]
	s_cmp_eq_u64 s[30:31], 0
	s_cbranch_scc1 .LBB0_1658
	s_mov_b64 s[44:45], -1
	s_cmp_eq_u64 s[22:23], 0
	s_cbranch_scc1 .LBB0_1655
	v_mfma_f32_16x16x32_bf16 v[10:13], v[142:145], v[174:177], v[10:13]
	s_mov_b64 s[44:45], 0
	v_mfma_f32_16x16x32_bf16 v[6:9], v[150:153], v[174:177], v[6:9]
	v_mfma_f32_16x16x32_bf16 v[10:13], v[146:149], v[178:181], v[10:13]
	v_mfma_f32_16x16x32_bf16 v[6:9], v[154:157], v[178:181], v[6:9]

; #define PG8_STAGEX(b, gbase) do { if constexpr (XR) { if (lane < 16) __builtin_amdgcn_global_load_lds((const unsigned*)((const char*)(gbase) + voffX), (PG8_LAS unsigned*)(lds + XR_OFF + (b) * 2048 + wid * 256), 16, 0, 0); } } while (0)
; #define PG8_MMAX() do { if constexpr (XR) { if (hasx) { __builtin_amdgcn_s_setprio(1); if (wr == 0) PG8_MMAX_(B0); else PG8_MMAX_(B1); __builtin_amdgcn_s_setprio(0); } } } while (0)
; #define PG8_WAIT_LOOP() do { if constexpr (XR) PG8_WAIT_V(9); else PG8_WAIT_V(8); } while (0)
; #define PG8_STAGE(bufoff, gbase, voff) do { _Pragma("unroll") for (int _i = 0; _i < 2; ++_i) \
;         __builtin_amdgcn_global_load_lds((const unsigned*)((const char*)(gbase) + (voff)[_i]), (PG8_LAS unsigned*)(lds + (bufoff) + ldsw + _i * 8192), 16, 0, 0); } while (0)
; #define PG8_LDA(dst, b, h) do { _Pragma("unroll") for (int m = 0; m < 4; ++m) _Pragma("unroll") for (int k = 0; k < 2; ++k) dst[m][k] = *(const PG8_LAS bf16x8*)(lds + PG8_SA(b, h) + aoff + m * 2048 + k * 1024); } while (0)
; #define PG8_MMA(ai, bj, At, Bt) do { __builtin_amdgcn_s_setprio(1); _Pragma("unroll") for (int m = 0; m < 4; ++m) _Pragma("unroll") for (int n = 0; n < 2; ++n) _Pragma("unroll") for (int k = 0; k < 2; ++k) \
;         acc[ai][bj][m][n] = __builtin_amdgcn_mfma_f32_16x16x32_bf16(Bt[n][k], At[m][k], acc[ai][bj][m][n], 0, 0, 0); __builtin_amdgcn_s_setprio(0); } while (0)
; #define PG8_WAIT_L(n) asm volatile("s_waitcnt lgkmcnt(" #n ")" ::: "memory")
; #define PG8_BAR __builtin_amdgcn_s_barrier()
; template <class Epi, class Sched, bool ALIGN_EPI = false, bool SP2 = false, bool DRAIN = true, bool XR = false>
; __device__ __forceinline__ void gemm_phase(PG8_LAS unsigned char* lds, const Gemm g, const Sched& S, const Epi& E) {
;     ...
;             const char* a1 = cA + PG8_KOA(t) + kstep;
;             const char* a2 = last ? nA + ka0 : cA + PG8_KOA(t + 2); const char* b2 = last ? nB + kb0 : cB + PG8_KOB(t + 2);
;             const char* x2 = XR ? (last ? nX + kx0 : cX + PG8_KOX(t + 2)) : nullptr; const char* x3 = XR ? x2 + kstep : nullptr;
;     ...
;             PG8_WAIT_LOOP(); PG8_WAIT_L(0); PG8_BAR; PG8_MMA(0, 0, At, B0); PG8_MMA(0, 1, At, B1); PG8_MMAX(); PG8_BAR; PG8_SCHED;
;             PG8_LDA(At, 0, 1); PG8_STAGE(PG8_SB(0, 0), b2, voffB); PG8_STAGE(PG8_SB(0, 1), b2 + hstep, voffB); PG8_STAGE(PG8_SA(0, 0), a2, voffA); PG8_STAGEX(0, x2);
.LBB0_1657:
.LBB0_1658:
	s_barrier
	v_cndmask_b32_e64 v2, 0, 1, s[30:31]
	v_cmp_ne_u32_e64 s[6:7], 1, v2
	v_cndmask_b32_e64 v2, 0, 1, s[22:23]
	v_cmp_ne_u32_e64 s[0:1], 1, v2
	s_add_i32 s46, s46, 2
	s_and_b32 s44, s46, s59
	s_lshr_b32 s84, s44, 2
	s_lshl_b32 s36, s44, 7
	s_lshl_b64 s[46:47], s[84:85], 17
	s_and_b32 s36, s36, 0x100
	s_add_u32 s45, s40, s46
	s_addc_u32 s46, s41, s47
	s_add_u32 s36, s45, s36
	s_mov_b32 s45, s85
	s_addc_u32 s46, s46, 0
	s_lshl_b64 s[44:45], s[44:45], 7
	s_add_u32 vcc_lo, s34, s44
	s_addc_u32 vcc_hi, s35, s45
	s_add_u32 s12, s42, s44
	s_addc_u32 s13, s43, s45
	s_cmp_eq_u32 s82, s89
	s_cselect_b32 s45, s39, s46
	s_cselect_b32 s44, s93, s36
	s_cselect_b32 s47, s90, s13
	s_cselect_b32 s46, s97, s12
	s_cselect_b32 vcc_hi, s96, vcc_hi
	s_cselect_b32 vcc_lo, s50, vcc_lo
	s_mov_b32 m0, s64
	v_lshl_add_u64 v[224:225], vcc, 0, v[216:217]
	v_lshl_add_u64 v[226:227], vcc, 0, v[220:221]
	s_add_u32 vcc_lo, vcc_lo, s8
	ds_read_b128 v[198:201], v249 offset:16384
	ds_read_b128 v[202:205], v249 offset:17408
	ds_read_b128 v[190:193], v249 offset:18432
	ds_read_b128 v[194:197], v249 offset:19456
	ds_read_b128 v[182:185], v249 offset:20480
	ds_read_b128 v[186:189], v249 offset:21504
	ds_read_b128 v[174:177], v249 offset:22528
	ds_read_b128 v[178:181], v249 offset:23552
	global_load_lds_dwordx4 v[224:225], off
	s_mov_b32 m0, s65
	s_addc_u32 vcc_hi, vcc_hi, s9
	global_load_lds_dwordx4 v[226:227], off
	v_lshl_add_u64 v[228:229], vcc, 0, v[216:217]
	s_mov_b32 m0, s67
	v_lshl_add_u64 v[230:231], vcc, 0, v[220:221]
	global_load_lds_dwordx4 v216, vcc
	s_mov_b32 m0, s68
	v_lshl_add_u64 v[232:233], s[44:45], 0, v[214:215]
	global_load_lds_dwordx4 v220, vcc
	s_mov_b32 m0, s63
	v_lshl_add_u64 v[234:235], s[44:45], 0, v[218:219]
	global_load_lds_dwordx4 v214, s[44:45]
	s_mov_b32 m0, s69
	v_lshl_add_u64 v[4:5], s[46:47], 0, v[222:223]
	global_load_lds_dwordx4 v218, s[44:45]
	s_and_saveexec_b64 s[46:47], s[2:3]
	s_cbranch_execz .LBB0_1660
	s_add_i32 s12, s60, 0
	s_add_i32 m0, s12, 0x22400
	s_nop 0
	global_load_lds_dwordx4 v[4:5], off

; #define PG8_LDX(b) do { if constexpr (XR) { _Pragma("unroll") for (int k = 0; k < 2; ++k) Ax_[k] = *(const PG8_LAS bf16x8*)(lds + XR_OFF + (b) * 2048 + aoffx + k * 1024); } } while (0)
; #define PG8_MMAX() do { if constexpr (XR) { if (hasx) { __builtin_amdgcn_s_setprio(1); if (wr == 0) PG8_MMAX_(B0); else PG8_MMAX_(B1); __builtin_amdgcn_s_setprio(0); } } } while (0)
; #define PG8_WAIT_LOOP() do { if constexpr (XR) PG8_WAIT_V(9); else PG8_WAIT_V(8); } while (0)
; #define PG8_STAGE(bufoff, gbase, voff) do { _Pragma("unroll") for (int _i = 0; _i < 2; ++_i) \
;         __builtin_amdgcn_global_load_lds((const unsigned*)((const char*)(gbase) + (voff)[_i]), (PG8_LAS unsigned*)(lds + (bufoff) + ldsw + _i * 8192), 16, 0, 0); } while (0)
; #define PG8_LDA(dst, b, h) do { _Pragma("unroll") for (int m = 0; m < 4; ++m) _Pragma("unroll") for (int k = 0; k < 2; ++k) dst[m][k] = *(const PG8_LAS bf16x8*)(lds + PG8_SA(b, h) + aoff + m * 2048 + k * 1024); } while (0)
; #define PG8_LDB(dst, b, h) do { _Pragma("unroll") for (int n = 0; n < 2; ++n) _Pragma("unroll") for (int k = 0; k < 2; ++k) dst[n][k] = *(const PG8_LAS bf16x8*)(lds + PG8_SB(b, h) + boff + n * 2048 + k * 1024); } while (0)
; #define PG8_MMA(ai, bj, At, Bt) do { __builtin_amdgcn_s_setprio(1); _Pragma("unroll") for (int m = 0; m < 4; ++m) _Pragma("unroll") for (int n = 0; n < 2; ++n) _Pragma("unroll") for (int k = 0; k < 2; ++k) \
;         acc[ai][bj][m][n] = __builtin_amdgcn_mfma_f32_16x16x32_bf16(Bt[n][k], At[m][k], acc[ai][bj][m][n], 0, 0, 0); __builtin_amdgcn_s_setprio(0); } while (0)
; #define PG8_WAIT_L(n) asm volatile("s_waitcnt lgkmcnt(" #n ")" ::: "memory")
; #define PG8_BAR __builtin_amdgcn_s_barrier()
; #define PG8_SCHED __builtin_amdgcn_sched_barrier(0)
; template <class Epi, class Sched, bool ALIGN_EPI = false, bool SP2 = false, bool DRAIN = true, bool XR = false>
; __device__ __forceinline__ void gemm_phase(PG8_LAS unsigned char* lds, const Gemm g, const Sched& S, const Epi& E) {
;     ...
;             PG8_LDB(B0, 0, 0); PG8_LDB(B1, 0, 1); PG8_SCHED; PG8_LDA(At, 0, 0); PG8_LDX(0); PG8_STAGE(PG8_SA(1, 1), a1 + hstepA, voffA);
;             PG8_WAIT_LOOP(); PG8_WAIT_L(0); PG8_BAR; PG8_MMA(0, 0, At, B0); PG8_MMA(0, 1, At, B1); PG8_MMAX(); PG8_BAR; PG8_SCHED;
.LBB0_1856:
	v_add_u32_e32 v2, 0x10000, v237
	s_add_i32 s56, s88, s45
	ds_read_b128 v[158:161], v2
	ds_read_b128 v[162:165], v2 offset:1024
	ds_read_b128 v[166:169], v2 offset:2048
	ds_read_b128 v[170:173], v2 offset:3072
	v_add_u32_e32 v2, 0x14000, v237
	s_and_b32 s8, s56, s67
	ds_read_b128 v[142:145], v2
	ds_read_b128 v[146:149], v2 offset:1024
	ds_read_b128 v[150:153], v2 offset:2048
	ds_read_b128 v[154:157], v2 offset:3072
	s_lshr_b32 s84, s8, 2
	s_lshl_b32 s8, s8, 7
	s_lshl_b64 s[0:1], s[84:85], 9
	s_and_b32 s8, s8, 0x100
	s_add_u32 s0, s24, s0
	s_addc_u32 s1, s25, s1
	s_add_u32 s0, s0, s8
	s_addc_u32 s1, s1, 0
	s_add_u32 s0, s0, s18
	s_addc_u32 s1, s1, s19
	v_lshl_add_u64 v[4:5], s[0:1], 0, v[214:215]
	v_add_u32_e32 v2, 0x22400, v239
	v_lshl_add_u64 v[4:5], v[4:5], 0, s[86:87]
	s_add_i32 m0, s72, 0xc000
	ds_read_b128 v[182:185], v238
	ds_read_b128 v[186:189], v238 offset:1024
	ds_read_b128 v[190:193], v238 offset:2048
	ds_read_b128 v[194:197], v238 offset:3072
	ds_read_b128 v[198:201], v238 offset:4096
	ds_read_b128 v[202:205], v238 offset:5120
	ds_read_b128 v[206:209], v238 offset:6144
	ds_read_b128 v[224:227], v238 offset:7168
	ds_read_b128 v[174:177], v2
	ds_read_b128 v[178:181], v2 offset:1024
	global_load_lds_dwordx4 v[4:5], off
	v_lshl_add_u64 v[4:5], s[0:1], 0, v[218:219]
	v_lshl_add_u64 v[4:5], v[4:5], 0, s[86:87]
	s_add_i32 m0, s72, 0xe000
	s_nop 0
	global_load_lds_dwordx4 v[4:5], off
	s_waitcnt vmcnt(9)
	s_waitcnt lgkmcnt(0)
	s_barrier
	v_mfma_f32_16x16x32_bf16 v[138:141], v[158:161], v[182:185], v[138:141]
	v_mfma_f32_16x16x32_bf16 v[134:137], v[166:169], v[182:185], v[134:137]
	v_mfma_f32_16x16x32_bf16 v[130:133], v[158:161], v[190:193], v[130:133]
	v_mfma_f32_16x16x32_bf16 v[126:129], v[166:169], v[190:193], v[126:129]
	v_mfma_f32_16x16x32_bf16 v[122:125], v[158:161], v[198:201], v[122:125]
	v_mfma_f32_16x16x32_bf16 v[118:121], v[166:169], v[198:201], v[118:121]
	v_mfma_f32_16x16x32_bf16 v[114:117], v[158:161], v[206:209], v[114:117]
	v_mfma_f32_16x16x32_bf16 v[110:113], v[166:169], v[206:209], v[110:113]
	v_mfma_f32_16x16x32_bf16 v[138:141], v[162:165], v[186:189], v[138:141]
	v_mfma_f32_16x16x32_bf16 v[134:137], v[170:173], v[186:189], v[134:137]
	v_mfma_f32_16x16x32_bf16 v[130:133], v[162:165], v[194:197], v[130:133]
	v_mfma_f32_16x16x32_bf16 v[126:129], v[170:173], v[194:197], v[126:129]
	v_mfma_f32_16x16x32_bf16 v[122:125], v[162:165], v[202:205], v[122:125]
	v_mfma_f32_16x16x32_bf16 v[118:121], v[170:173], v[202:205], v[118:121]
	v_mfma_f32_16x16x32_bf16 v[114:117], v[162:165], v[224:227], v[114:117]
	v_mfma_f32_16x16x32_bf16 v[110:113], v[170:173], v[224:227], v[110:113]
	v_mfma_f32_16x16x32_bf16 v[106:109], v[142:145], v[182:185], v[106:109]
	v_mfma_f32_16x16x32_bf16 v[102:105], v[150:153], v[182:185], v[102:105]
	v_mfma_f32_16x16x32_bf16 v[98:101], v[142:145], v[190:193], v[98:101]
	v_mfma_f32_16x16x32_bf16 v[94:97], v[150:153], v[190:193], v[94:97]
	v_mfma_f32_16x16x32_bf16 v[90:93], v[142:145], v[198:201], v[90:93]
	v_mfma_f32_16x16x32_bf16 v[86:89], v[150:153], v[198:201], v[86:89]
	v_mfma_f32_16x16x32_bf16 v[82:85], v[142:145], v[206:209], v[82:85]
	v_mfma_f32_16x16x32_bf16 v[78:81], v[150:153], v[206:209], v[78:81]
	v_mfma_f32_16x16x32_bf16 v[106:109], v[146:149], v[186:189], v[106:109]
	v_mfma_f32_16x16x32_bf16 v[102:105], v[154:157], v[186:189], v[102:105]
	v_mfma_f32_16x16x32_bf16 v[98:101], v[146:149], v[194:197], v[98:101]
	v_mfma_f32_16x16x32_bf16 v[94:97], v[154:157], v[194:197], v[94:97]
	v_mfma_f32_16x16x32_bf16 v[90:93], v[146:149], v[202:205], v[90:93]
	v_mfma_f32_16x16x32_bf16 v[86:89], v[154:157], v[202:205], v[86:89]
	v_mfma_f32_16x16x32_bf16 v[82:85], v[146:149], v[224:227], v[82:85]
	v_mfma_f32_16x16x32_bf16 v[78:81], v[154:157], v[224:227], v[78:81]
	s_cmp_eq_u64 s[40:41], 0
	s_cbranch_scc1 .LBB0_1862
	s_mov_b64 s[54:55], -1
	s_cmp_eq_u64 s[46:47], 0
	s_cbranch_scc1 .LBB0_1859
	v_mfma_f32_16x16x32_bf16 v[10:13], v[142:145], v[174:177], v[10:13]
	s_mov_b64 s[54:55], 0
	v_mfma_f32_16x16x32_bf16 v[6:9], v[150:153], v[174:177], v[6:9]
	v_mfma_f32_16x16x32_bf16 v[10:13], v[146:149], v[178:181], v[10:13]
	v_mfma_f32_16x16x32_bf16 v[6:9], v[154:157], v[178:181], v[6:9]

; #define PG8_STAGEX(b, gbase) do { if constexpr (XR) { if (lane < 16) __builtin_amdgcn_global_load_lds((const unsigned*)((const char*)(gbase) + voffX), (PG8_LAS unsigned*)(lds + XR_OFF + (b) * 2048 + wid * 256), 16, 0, 0); } } while (0)
; #define PG8_MMAX() do { if constexpr (XR) { if (hasx) { __builtin_amdgcn_s_setprio(1); if (wr == 0) PG8_MMAX_(B0); else PG8_MMAX_(B1); __builtin_amdgcn_s_setprio(0); } } } while (0)
; #define PG8_WAIT_LOOP() do { if constexpr (XR) PG8_WAIT_V(9); else PG8_WAIT_V(8); } while (0)
; #define PG8_STAGE(bufoff, gbase, voff) do { _Pragma("unroll") for (int _i = 0; _i < 2; ++_i) \
;         __builtin_amdgcn_global_load_lds((const unsigned*)((const char*)(gbase) + (voff)[_i]), (PG8_LAS unsigned*)(lds + (bufoff) + ldsw + _i * 8192), 16, 0, 0); } while (0)
; #define PG8_LDA(dst, b, h) do { _Pragma("unroll") for (int m = 0; m < 4; ++m) _Pragma("unroll") for (int k = 0; k < 2; ++k) dst[m][k] = *(const PG8_LAS bf16x8*)(lds + PG8_SA(b, h) + aoff + m * 2048 + k * 1024); } while (0)
; #define PG8_MMA(ai, bj, At, Bt) do { __builtin_amdgcn_s_setprio(1); _Pragma("unroll") for (int m = 0; m < 4; ++m) _Pragma("unroll") for (int n = 0; n < 2; ++n) _Pragma("unroll") for (int k = 0; k < 2; ++k) \
;         acc[ai][bj][m][n] = __builtin_amdgcn_mfma_f32_16x16x32_bf16(Bt[n][k], At[m][k], acc[ai][bj][m][n], 0, 0, 0); __builtin_amdgcn_s_setprio(0); } while (0)
; #define PG8_WAIT_L(n) asm volatile("s_waitcnt lgkmcnt(" #n ")" ::: "memory")
; #define PG8_BAR __builtin_amdgcn_s_barrier()
; template <class Epi, class Sched, bool ALIGN_EPI = false, bool SP2 = false, bool DRAIN = true, bool XR = false>
; __device__ __forceinline__ void gemm_phase(PG8_LAS unsigned char* lds, const Gemm g, const Sched& S, const Epi& E) {
;     ...
;             const char* a1 = cA + PG8_KOA(t) + kstep;
;             const char* a2 = last ? nA + ka0 : cA + PG8_KOA(t + 2); const char* b2 = last ? nB + kb0 : cB + PG8_KOB(t + 2);
;             const char* x2 = XR ? (last ? nX + kx0 : cX + PG8_KOX(t + 2)) : nullptr; const char* x3 = XR ? x2 + kstep : nullptr;
;     ...
;             PG8_WAIT_LOOP(); PG8_WAIT_L(0); PG8_BAR; PG8_MMA(0, 0, At, B0); PG8_MMA(0, 1, At, B1); PG8_MMAX(); PG8_BAR; PG8_SCHED;
;             PG8_LDA(At, 0, 1); PG8_STAGE(PG8_SB(0, 0), b2, voffB); PG8_STAGE(PG8_SB(0, 1), b2 + hstep, voffB); PG8_STAGE(PG8_SA(0, 0), a2, voffA); PG8_STAGEX(0, x2);
.LBB0_1861:
.LBB0_1862:
	s_barrier
	v_cndmask_b32_e64 v2, 0, 1, s[40:41]
	v_cmp_ne_u32_e64 s[8:9], 1, v2
	v_cndmask_b32_e64 v2, 0, 1, s[46:47]
	v_cmp_ne_u32_e64 s[0:1], 1, v2
	s_add_i32 s56, s56, 2
	s_and_b32 s54, s56, s67
	s_lshr_b32 s84, s54, 2
	s_lshl_b32 s36, s54, 7
	s_lshl_b64 s[56:57], s[84:85], 9
	s_and_b32 s36, s36, 0x100
	s_add_u32 s55, s24, s56
	s_addc_u32 s56, s25, s57
	s_add_u32 s36, s55, s36
	s_mov_b32 s55, s85
	s_addc_u32 s56, s56, 0
	s_lshl_b64 s[54:55], s[54:55], 7
	s_add_u32 vcc_lo, s22, s54
	s_addc_u32 vcc_hi, s23, s55
	s_add_u32 s70, s28, s54
	s_addc_u32 s57, s29, s55
	s_cmp_eq_u32 s63, s45
	s_cselect_b32 s55, s59, s56
	s_cselect_b32 s54, s58, s36
	s_cselect_b32 s57, s44, s57
	s_cselect_b32 s56, s43, s70
	s_cselect_b32 vcc_hi, s42, vcc_hi
	s_cselect_b32 vcc_lo, s78, vcc_lo
	s_mov_b32 m0, s73
	v_lshl_add_u64 v[224:225], vcc, 0, v[216:217]
	v_lshl_add_u64 v[226:227], vcc, 0, v[220:221]
	s_add_u32 vcc_lo, vcc_lo, s18
	ds_read_b128 v[198:201], v238 offset:16384
	ds_read_b128 v[202:205], v238 offset:17408
	ds_read_b128 v[190:193], v238 offset:18432
	ds_read_b128 v[194:197], v238 offset:19456
	ds_read_b128 v[182:185], v238 offset:20480
	ds_read_b128 v[186:189], v238 offset:21504
	ds_read_b128 v[174:177], v238 offset:22528
	ds_read_b128 v[178:181], v238 offset:23552
	global_load_lds_dwordx4 v[224:225], off
	s_mov_b32 m0, s74
	s_addc_u32 vcc_hi, vcc_hi, s19
	global_load_lds_dwordx4 v[226:227], off
	v_lshl_add_u64 v[228:229], vcc, 0, v[216:217]
	s_mov_b32 m0, s75
	v_lshl_add_u64 v[230:231], vcc, 0, v[220:221]
	global_load_lds_dwordx4 v216, vcc
	s_mov_b32 m0, s76
	v_lshl_add_u64 v[232:233], s[54:55], 0, v[214:215]
	global_load_lds_dwordx4 v220, vcc
	s_mov_b32 m0, s72
	v_lshl_add_u64 v[234:235], s[54:55], 0, v[218:219]
	global_load_lds_dwordx4 v214, s[54:55]
	s_mov_b32 m0, s77
	v_lshl_add_u64 v[4:5], s[56:57], 0, v[222:223]
	global_load_lds_dwordx4 v218, s[54:55]
	s_and_saveexec_b64 s[56:57], s[2:3]
	s_cbranch_execz .LBB0_1864
	s_add_i32 s36, s68, 0
	s_add_i32 m0, s36, 0x22400
	s_nop 0
	global_load_lds_dwordx4 v[4:5], off
